# SSD scan and attention items: no static s_setprio raise for waves 4..7 (SIMD partners share issue evenly); QK groups read K and bias one group ahead
# speedup vs baseline: 1.0046x; 1.0011x over previous
; #define ATT_ISSUE(kt_) do { const int ktn_ = (kt_); ATT_LD(0, pk0, pv0); ATT_LD(1, pk1, pv1); ATT_LD(2, pk2_, pv2); ATT_LD(3, pk3, pv3); } while (0)
; __device__ __forceinline__ void attn_item(const Params& P, const int pass, const int item, const int wvi) {
;     ...
;   if (tid < 257) fb[tid] = lptr(P.rel_bias)[(int)P.bucket[tid] * 16 + h];
;   bf16x8 qf[4];
; #pragma unroll
;   for (int kk = 0; kk < 4; ++kk) qf[kk] = *(const bf16x8*)(qbuf + (size_t)(qb + w * 16 + fr) * DM + h * 128 + kk * 32 + fq * 8);
;   float mrun = lptr(P.attn_sink)[h], lrun = 1.f;
;   f32x4 oacc[8];
; #pragma unroll
;   for (int i = 0; i < 8; ++i) oacc[i] = f32x4{0.f, 0.f, 0.f, 0.f};
;   const float scale = 0.08838834764831845f;
;   const int qi = w * 16 + fr;
;   const int kt_lo = (nb == 0) ? 1 : 0, kt_hi = (nb == nbs - 1) ? 1 : 2;
;   uint4 pk0, pk1, pk2_, pk3, pv0, pv1, pv2, pv3;
;     ...
;   if (w >= 4) __builtin_amdgcn_s_setprio(1);
;   ATT_ISSUE(kt_lo);
.LBB0_557:
	s_or_b64 exec, exec, s[0:1]
	s_sub_i32 s0, s12, s24
	s_and_b32 s0, s0, -16
	v_readlane_b32 s1, v242, 4
	s_add_i32 s0, s0, s1
	s_lshl_b32 s1, s0, 3
	v_readlane_b32 s3, v244, 28
	v_and_b32_e32 v48, 15, v100
	s_add_i32 s1, s1, s3
	v_or_b32_e32 v0, s1, v48
	v_ashrrev_i32_e32 v1, 31, v0
	v_lshlrev_b64 v[0:1], 12, v[0:1]
	v_lshl_add_u64 v[0:1], s[62:63], 0, v[0:1]
	s_lshl_b32 s18, s2, 8
	v_lshl_add_u64 v[84:85], v[0:1], 0, s[18:19]
	v_and_b32_e32 v144, 48, v100
	v_lshl_add_u64 v[12:13], v[84:85], 0, v[144:145]
	global_load_dwordx4 v[0:3], v[12:13], off
	global_load_dwordx4 v[4:7], v[12:13], off offset:64
	global_load_dwordx4 v[8:11], v[12:13], off offset:128
	s_nop 0
	global_load_dwordx4 v[12:15], v[12:13], off offset:192
	s_lshl_b32 s1, s2, 2
	v_readlane_b32 s4, v244, 52
	v_mov_b32_e32 v16, s1
	v_readlane_b32 s6, v244, 54
	v_readlane_b32 s7, v244, 55
	v_readlane_b32 s5, v244, 53
	v_readlane_b32 s4, v245, 8
	v_readlane_b32 s5, v245, 9
	s_andn2_b64 vcc, exec, s[4:5]
	s_nop 0
	global_load_dword v117, v16, s[6:7]
	s_cbranch_vccnz .LBB0_559
.LBB0_559:
	s_ashr_i32 s0, s0, 4
	s_abs_i32 s3, s0
	v_readlane_b32 s4, v243, 59
	s_mul_hi_u32 s4, s3, s4
	s_mul_i32 s5, s4, s34
	s_sub_i32 s3, s3, s5
	s_ashr_i32 s1, s0, 31
	s_add_i32 s5, s4, 1
	s_sub_i32 s6, s3, s34
	s_cmp_ge_u32 s3, s34
	s_cselect_b32 s4, s5, s4
	s_cselect_b32 s3, s6, s3
	s_add_i32 s5, s4, 1
	s_cmp_ge_u32 s3, s34
	s_cselect_b32 s3, s5, s4
	s_xor_b32 s3, s3, s1
	s_sub_i32 s3, s3, s1
	s_mul_i32 s1, s3, s34
	s_sub_i32 s8, s0, s1
	s_cmp_eq_u32 s8, 0
	v_readlane_b32 s4, v243, 41
	s_cselect_b64 s[0:1], -1, 0
	s_cmp_eq_u32 s8, s4
	v_readlane_b32 s5, v243, 56
	s_cselect_b32 s4, 1, 2
	s_lshl_b32 s5, s3, s5
	s_ashr_i32 s6, s5, 31
	s_add_i32 s7, s8, -1
	s_cmp_lg_u64 s[0:1], 0
	v_cndmask_b32_e64 v49, 0, 1, s[0:1]
	s_addc_u32 s0, s8, -1
	s_ashr_i32 s1, s0, 31
	v_ashrrev_i32_e32 v86, 4, v40
	s_lshl_b64 s[0:1], s[0:1], 7
	v_add_u32_e32 v24, 0x200, v40
	v_add_u32_e32 v32, 0x400, v40
	v_add_u32_e32 v40, 0x600, v40
	s_add_u32 s0, s0, s5
	v_ashrrev_i32_e32 v90, 4, v24
	v_ashrrev_i32_e32 v92, 4, v32
	v_ashrrev_i32_e32 v94, 4, v40
	s_addc_u32 s1, s1, s6
	v_ashrrev_i32_e32 v87, 31, v86
	s_lshl_b32 s2, s2, 6
	v_ashrrev_i32_e32 v91, 31, v90
	v_ashrrev_i32_e32 v93, 31, v92
	v_ashrrev_i32_e32 v95, 31, v94
	v_lshl_add_u64 v[16:17], s[0:1], 0, v[86:87]
	v_readlane_b32 s10, v245, 21
	s_and_b32 s18, s2, 0x300
	v_readlane_b32 s2, v245, 23
	v_lshl_add_u64 v[24:25], s[0:1], 0, v[90:91]
	v_lshl_add_u64 v[32:33], s[0:1], 0, v[92:93]
	v_lshl_add_u64 v[40:41], s[0:1], 0, v[94:95]
	v_lshlrev_b64 v[16:17], 10, v[16:17]
	v_readlane_b32 s11, v245, 22
	v_lshlrev_b32_e32 v20, 3, v100
	v_readlane_b32 s3, v245, 24
	v_lshlrev_b64 v[24:25], 10, v[24:25]
	v_lshlrev_b64 v[32:33], 10, v[32:33]
	v_lshlrev_b64 v[40:41], 10, v[40:41]
	v_lshl_add_u64 v[18:19], s[10:11], 0, v[16:17]
	v_and_b32_e32 v20, 0x78, v20
	v_lshl_add_u64 v[16:17], s[2:3], 0, v[16:17]
	v_lshl_add_u64 v[26:27], s[10:11], 0, v[24:25]
	v_lshl_add_u64 v[24:25], s[2:3], 0, v[24:25]
	v_lshl_add_u64 v[34:35], s[10:11], 0, v[32:33]
	v_lshl_add_u64 v[32:33], s[2:3], 0, v[32:33]
	v_lshl_add_u64 v[42:43], s[10:11], 0, v[40:41]
	v_lshl_add_u64 v[40:41], s[2:3], 0, v[40:41]
	v_lshl_add_u64 v[18:19], v[18:19], 0, s[18:19]
	v_lshlrev_b32_e32 v88, 1, v20
	v_mov_b32_e32 v89, v145
	v_lshl_add_u64 v[16:17], v[16:17], 0, s[18:19]
	v_lshl_add_u64 v[26:27], v[26:27], 0, s[18:19]
	v_lshl_add_u64 v[24:25], v[24:25], 0, s[18:19]
	v_lshl_add_u64 v[34:35], v[34:35], 0, s[18:19]
	v_lshl_add_u64 v[32:33], v[32:33], 0, s[18:19]
	v_lshl_add_u64 v[42:43], v[42:43], 0, s[18:19]
	v_lshl_add_u64 v[40:41], v[40:41], 0, s[18:19]
	v_lshl_add_u64 v[18:19], v[18:19], 0, v[88:89]
	v_lshl_add_u64 v[20:21], v[16:17], 0, v[88:89]
	v_lshl_add_u64 v[26:27], v[26:27], 0, v[88:89]
	v_lshl_add_u64 v[28:29], v[24:25], 0, v[88:89]
	v_lshl_add_u64 v[34:35], v[34:35], 0, v[88:89]
	v_lshl_add_u64 v[36:37], v[32:33], 0, v[88:89]
	v_lshl_add_u64 v[42:43], v[42:43], 0, v[88:89]
	s_waitcnt vmcnt(9)
	v_lshl_add_u64 v[44:45], v[40:41], 0, v[88:89]
	global_load_dwordx4 v[16:19], v[18:19], off
	s_nop 0
	global_load_dwordx4 v[20:23], v[20:21], off
	s_nop 0
	global_load_dwordx4 v[24:27], v[26:27], off
	s_nop 0
	global_load_dwordx4 v[28:31], v[28:29], off
	s_nop 0
	global_load_dwordx4 v[32:35], v[34:35], off
	s_nop 0
	global_load_dwordx4 v[36:39], v[36:37], off
	s_nop 0
	global_load_dwordx4 v[40:43], v[42:43], off
	s_nop 0
	global_load_dwordx4 v[44:47], v[44:45], off
	s_movk_i32 s0, 0x120
	s_movk_i32 s1, 0x110
	v_mul_lo_u32 v102, v86, s0
	v_mul_lo_u32 v104, v90, s0
	v_mul_lo_u32 v106, v92, s0
	v_mul_lo_u32 v108, v94, s0
	s_add_u32 s0, s10, s18
	v_mul_lo_u32 v101, v86, s1
	v_mul_lo_u32 v103, v90, s1
	v_mul_lo_u32 v105, v92, s1
	v_mul_lo_u32 v107, v94, s1
	s_addc_u32 s1, s11, 0
	v_and_b32_e32 v50, 63, v100
	v_lshl_add_u64 v[96:97], s[0:1], 0, v[88:89]
	s_add_u32 s0, s2, s18
	v_bfe_u32 v51, v100, 4, 2
	s_addc_u32 s1, s3, 0
	v_lshlrev_b32_e32 v50, 2, v50
	v_lshl_add_u64 v[98:99], s[0:1], 0, v[88:89]
	v_lshlrev_b32_e32 v89, 2, v51
	v_xor_b32_e32 v109, 64, v50
	v_xor_b32_e32 v110, 0x80, v50
	v_lshrrev_b32_e32 v50, 2, v48
	v_or_b32_e32 v50, v89, v50
	v_mul_u32_u24_e32 v112, 0x120, v50
	v_lshlrev_b32_e32 v50, 7, v49
	v_readlane_b32 s0, v244, 29
	v_readfirstlane_b32 s8, v49
	v_mul_u32_u24_e32 v111, 0x110, v48
	v_add_u32_e32 v50, s0, v50
	v_add_u32_e32 v50, v50, v89
	v_sub_u32_e32 v113, v50, v48
	v_lshlrev_b32_e32 v50, 4, v51
	v_lshl_or_b32 v49, v49, 9, v50
	v_lshlrev_b32_e32 v48, 2, v48
	s_waitcnt vmcnt(16)
	v_lshlrev_b32_e32 v52, 2, v100
	v_sub_u32_e32 v48, v49, v48
	v_readlane_b32 s0, v244, 27
	v_and_b32_e32 v52, 12, v52
	v_mov_b32_e32 v116, 1.0
	v_add_u32_e32 v114, s0, v48
	v_add_u32_e32 v114, 0x11fc, v114
	v_mov_b32_e32 v48, 0
	v_lshlrev_b32_e32 v115, 1, v52
	v_mov_b32_e32 v49, v48
	v_mov_b32_e32 v50, v48
	v_mov_b32_e32 v51, v48
	v_mov_b32_e32 v56, v48
	v_mov_b32_e32 v57, v48
	v_mov_b32_e32 v58, v48
	v_mov_b32_e32 v59, v48
	v_mov_b32_e32 v52, v48
	v_mov_b32_e32 v53, v48
	v_mov_b32_e32 v54, v48
	v_mov_b32_e32 v55, v48
	v_mov_b32_e32 v60, v48
	v_mov_b32_e32 v61, v48
	v_mov_b32_e32 v62, v48
	v_mov_b32_e32 v63, v48
	v_mov_b32_e32 v64, v48
	v_mov_b32_e32 v65, v48
	v_mov_b32_e32 v66, v48
	v_mov_b32_e32 v67, v48
	v_mov_b32_e32 v68, v48
	v_mov_b32_e32 v69, v48
	v_mov_b32_e32 v70, v48
	v_mov_b32_e32 v71, v48
	v_mov_b32_e32 v72, v48
	v_mov_b32_e32 v73, v48
	v_mov_b32_e32 v74, v48
	v_mov_b32_e32 v75, v48
	v_mov_b32_e32 v76, v48
	v_mov_b32_e32 v77, v48
	v_mov_b32_e32 v78, v48
	v_mov_b32_e32 v79, v48
; #define ATT_ISSUE(kt_) do { const int ktn_ = (kt_); ATT_LD(0, pk0, pv0); ATT_LD(1, pk1, pv1); ATT_LD(2, pk2_, pv2); ATT_LD(3, pk3, pv3); } while (0)
; #define ATT_ST(i, RK, RV) do { const int q = tid + NTHR * (i), row = q >> 4, c16 = q & 15; \
;       *(uint4*)(Ks + row * LDP + c16 * 8) = RK; *(uint4*)(Vs + row * LDV + c16 * 8) = RV; } while (0)
; __device__ __forceinline__ void attn_item(const Params& P, const int pass, const int item, const int wvi) {
;     ...
;   for (int kt = kt_lo; kt <= kt_hi; ++kt) {
;     u16* Ks = (u16*)(smem + (kt & 1) * ATT_SET);
;     u16* Vs = Ks + 128 * LDP;
;     ATT_ST(0, pk0, pv0); ATT_ST(1, pk1, pv1); ATT_ST(2, pk2_, pv2); ATT_ST(3, pk3, pv3);
;     __syncthreads();
;     ATT_ISSUE((kt < kt_hi) ? kt + 1 : kt);
;     f32x4 sc[8];
;     float mx = -INFINITY;
; #pragma unroll
;     for (int t8 = 0; t8 < 8; ++t8) {
;       f32x4 a = f32x4{0.f, 0.f, 0.f, 0.f};
; #pragma unroll
;       for (int kk = 0; kk < 4; ++kk) {
;         bf16x8 kf = *(const bf16x8*)(Ks + (t8 * 16 + fr) * LDP + kk * 32 + fq * 8);
;         a = __builtin_amdgcn_mfma_f32_16x16x32_bf16(kf, qf[kk], a, 0, 0, 0);
;       }
; #pragma unroll
;       for (int j = 0; j < 4; ++j) {
;         const int rel = (kt - 1) * 128 + t8 * 16 + fq * 4 + j - qi;
;         const bool ok = (rel >= -128) && (rel <= 128);
;         const int ri = ok ? rel + 128 : 0;
;         const float v = ok ? (a[j] * scale + fb[ri]) : -INFINITY;
;         a[j] = v;
;         mx = fmaxf(mx, v);
;       }
;       sc[t8] = a;
.LBB0_560:
	s_bitcmp1_b32 s8, 0
	s_cselect_b32 s0, 0x11800, 0
	s_add_i32 s9, s0, 32
	s_cmp_ge_u32 s8, s4
	s_mov_b32 s2, s8
	v_add3_u32 v80, s9, v101, v88
	s_cselect_b64 s[0:1], -1, 0
	s_add_i32 s8, s8, 1
	s_waitcnt vmcnt(7)
	ds_write_b128 v80, v[16:19]
	v_add3_u32 v16, s9, v102, v88
	s_cmp_lt_u32 s2, s4
	s_waitcnt vmcnt(6)
	ds_write_b128 v16, v[20:23] offset:34816
	v_add3_u32 v16, s9, v103, v88
	s_cselect_b32 s2, s8, s2
	s_waitcnt vmcnt(5)
	ds_write_b128 v16, v[24:27]
	v_add3_u32 v16, s9, v104, v88
	s_add_i32 s2, s2, s7
	s_waitcnt vmcnt(4)
	ds_write_b128 v16, v[28:31] offset:34816
	v_add3_u32 v16, s9, v105, v88
	s_ashr_i32 s3, s2, 31
	s_waitcnt vmcnt(3)
	ds_write_b128 v16, v[32:35]
	v_add3_u32 v16, s9, v106, v88
	s_lshl_b64 s[2:3], s[2:3], 7
	s_waitcnt vmcnt(2)
	ds_write_b128 v16, v[36:39] offset:34816
	v_add3_u32 v16, s9, v107, v88
	s_add_u32 s2, s2, s5
	s_waitcnt vmcnt(1)
	ds_write_b128 v16, v[40:43]
	v_add3_u32 v16, s9, v108, v88
	s_addc_u32 s3, s3, s6
	s_waitcnt vmcnt(0)
	ds_write_b128 v16, v[44:47] offset:34816
	v_lshl_add_u64 v[16:17], s[2:3], 0, v[86:87]
	v_lshlrev_b64 v[16:17], 10, v[16:17]
	v_add_u32_e32 v28, s9, v144
	v_lshl_add_u64 v[18:19], v[96:97], 0, v[16:17]
	v_lshl_add_u64 v[20:21], v[98:99], 0, v[16:17]
	v_add_u32_e32 v126, v28, v111
	s_waitcnt lgkmcnt(0)
	s_barrier
	ds_read_b32 v210, v114
	ds_read_b32 v211, v114 offset:4
	ds_read_b32 v212, v114 offset:8
	ds_read_b32 v213, v114 offset:12
	global_load_dwordx4 v[16:19], v[18:19], off
	s_nop 0
	global_load_dwordx4 v[20:23], v[20:21], off
	ds_read_b128 v[32:35], v126
	v_lshl_add_u64 v[24:25], s[2:3], 0, v[90:91]
	v_lshlrev_b64 v[24:25], 10, v[24:25]
	v_lshl_add_u64 v[26:27], v[96:97], 0, v[24:25]
	v_lshl_add_u64 v[28:29], v[98:99], 0, v[24:25]
	global_load_dwordx4 v[24:27], v[26:27], off
	s_nop 0
	global_load_dwordx4 v[28:31], v[28:29], off
	ds_read_b128 v[40:43], v126 offset:64
	ds_read_b128 v[80:83], v126 offset:128
	s_waitcnt lgkmcnt(2)
	v_mfma_f32_16x16x32_bf16 v[44:47], v[32:35], v[0:3], 0
	v_lshl_add_u64 v[36:37], s[2:3], 0, v[92:93]
	v_lshl_add_u64 v[118:119], s[2:3], 0, v[94:95]
	v_lshlrev_b64 v[36:37], 10, v[36:37]
	s_waitcnt lgkmcnt(1)
	v_mfma_f32_16x16x32_bf16 v[40:43], v[40:43], v[4:7], v[44:47]
	v_lshlrev_b64 v[118:119], 10, v[118:119]
	v_lshl_add_u64 v[38:39], v[96:97], 0, v[36:37]
	v_lshl_add_u64 v[36:37], v[98:99], 0, v[36:37]
	v_lshl_add_u64 v[44:45], v[96:97], 0, v[118:119]
	v_lshl_add_u64 v[46:47], v[98:99], 0, v[118:119]
	global_load_dwordx4 v[32:35], v[38:39], off
	s_nop 0
	global_load_dwordx4 v[36:39], v[36:37], off
	ds_read_b128 v[118:121], v126 offset:192
	s_waitcnt lgkmcnt(1)
	v_mfma_f32_16x16x32_bf16 v[80:83], v[80:83], v[8:11], v[40:43]
	s_nop 2
	global_load_dwordx4 v[40:43], v[44:45], off
	s_nop 0
	global_load_dwordx4 v[44:47], v[46:47], off
	v_cmp_gt_u32_e32 vcc, s97, v113
	s_waitcnt lgkmcnt(0)
	v_mfma_f32_16x16x32_bf16 v[80:83], v[118:121], v[12:15], v[80:83]
	ds_read_b128 v[176:179], v126 offset:4352
	ds_read_b128 v[180:183], v126 offset:4416
	ds_read_b128 v[190:193], v126 offset:4480
	ds_read_b128 v[218:221], v126 offset:4544
	ds_read_b32 v214, v114 offset:64
	ds_read_b32 v215, v114 offset:68
	ds_read_b32 v216, v114 offset:72
	ds_read_b32 v217, v114 offset:76
	v_fmamk_f32 v121, v80, 0x3db504f3, v210
	v_fmamk_f32 v118, v81, 0x3db504f3, v211
	v_fmamk_f32 v124, v82, 0x3db504f3, v212
	v_fmamk_f32 v119, v83, 0x3db504f3, v213
	s_waitcnt lgkmcnt(0)
	v_mfma_f32_16x16x32_bf16 v[80:83], v[176:179], v[0:3], 0
	v_mfma_f32_16x16x32_bf16 v[80:83], v[180:183], v[4:7], v[80:83]
	v_mfma_f32_16x16x32_bf16 v[80:83], v[190:193], v[8:11], v[80:83]
	v_mfma_f32_16x16x32_bf16 v[80:83], v[218:221], v[12:15], v[80:83]
	ds_read_b128 v[222:225], v126 offset:8704
	ds_read_b128 v[226:229], v126 offset:8768
	ds_read_b128 v[230:233], v126 offset:8832
	ds_read_b128 v[234:237], v126 offset:8896
	ds_read_b32 v210, v114 offset:128
	ds_read_b32 v211, v114 offset:132
	ds_read_b32 v212, v114 offset:136
	ds_read_b32 v213, v114 offset:140
	v_fmamk_f32 v122, v80, 0x3db504f3, v214
	v_fmamk_f32 v120, v81, 0x3db504f3, v215
	v_fmamk_f32 v125, v82, 0x3db504f3, v216
	v_fmamk_f32 v123, v83, 0x3db504f3, v217
	s_waitcnt lgkmcnt(0)
	v_mfma_f32_16x16x32_bf16 v[80:83], v[222:225], v[0:3], 0
	v_mfma_f32_16x16x32_bf16 v[80:83], v[226:229], v[4:7], v[80:83]
	v_mfma_f32_16x16x32_bf16 v[80:83], v[230:233], v[8:11], v[80:83]
	v_mfma_f32_16x16x32_bf16 v[80:83], v[234:237], v[12:15], v[80:83]
	ds_read_b128 v[176:179], v126 offset:13056
	ds_read_b128 v[180:183], v126 offset:13120
	ds_read_b128 v[190:193], v126 offset:13184
	ds_read_b128 v[218:221], v126 offset:13248
	ds_read_b32 v214, v114 offset:192
	ds_read_b32 v215, v114 offset:196
	ds_read_b32 v216, v114 offset:200
	ds_read_b32 v217, v114 offset:204
	v_fmamk_f32 v128, v80, 0x3db504f3, v210
	v_fmamk_f32 v127, v81, 0x3db504f3, v211
	v_fmamk_f32 v130, v82, 0x3db504f3, v212
	v_fmamk_f32 v129, v83, 0x3db504f3, v213
	s_waitcnt lgkmcnt(0)
	v_mfma_f32_16x16x32_bf16 v[80:83], v[176:179], v[0:3], 0
	v_mfma_f32_16x16x32_bf16 v[80:83], v[180:183], v[4:7], v[80:83]
	v_mfma_f32_16x16x32_bf16 v[80:83], v[190:193], v[8:11], v[80:83]
	v_mfma_f32_16x16x32_bf16 v[80:83], v[218:221], v[12:15], v[80:83]
	ds_read_b128 v[222:225], v126 offset:17408
	ds_read_b128 v[226:229], v126 offset:17472
	ds_read_b128 v[230:233], v126 offset:17536
	ds_read_b128 v[234:237], v126 offset:17600
	ds_read_b32 v210, v114 offset:256
	ds_read_b32 v211, v114 offset:260
	ds_read_b32 v212, v114 offset:264
	ds_read_b32 v213, v114 offset:268
	v_fmamk_f32 v136, v80, 0x3db504f3, v214
	v_fmamk_f32 v131, v81, 0x3db504f3, v215
	v_fmamk_f32 v138, v82, 0x3db504f3, v216
	v_fmamk_f32 v139, v83, 0x3db504f3, v217
	s_waitcnt lgkmcnt(0)
; __device__ __forceinline__ void attn_item(const Params& P, const int pass, const int item, const int wvi) {
;     ...
;     for (int t8 = 0; t8 < 8; ++t8) {
;       f32x4 a = f32x4{0.f, 0.f, 0.f, 0.f};
; #pragma unroll
;       for (int kk = 0; kk < 4; ++kk) {
;         bf16x8 kf = *(const bf16x8*)(Ks + (t8 * 16 + fr) * LDP + kk * 32 + fq * 8);
;         a = __builtin_amdgcn_mfma_f32_16x16x32_bf16(kf, qf[kk], a, 0, 0, 0);
;       }
; #pragma unroll
;       for (int j = 0; j < 4; ++j) {
;         const int rel = (kt - 1) * 128 + t8 * 16 + fq * 4 + j - qi;
;         const bool ok = (rel >= -128) && (rel <= 128);
;         const int ri = ok ? rel + 128 : 0;
;         const float v = ok ? (a[j] * scale + fb[ri]) : -INFINITY;
;         a[j] = v;
;         mx = fmaxf(mx, v);
;       }
;       sc[t8] = a;
;     }
;     mx = fmaxf(mx, shfl_src(mx, lane ^ 16));
;     mx = fmaxf(mx, shfl_src(mx, lane ^ 32));
;     const float mnew = fmaxf(mrun, mx);
;     const float alpha = __expf(mrun - mnew);
;     float psum = 0.f;
; #pragma unroll
;     for (int t8 = 0; t8 < 8; ++t8)
; #pragma unroll
;       for (int j = 0; j < 4; ++j) { const float pv = __expf(sc[t8][j] - mnew); sc[t8][j] = pv; psum += pv; }
	v_mfma_f32_16x16x32_bf16 v[80:83], v[222:225], v[0:3], 0
	v_mfma_f32_16x16x32_bf16 v[80:83], v[226:229], v[4:7], v[80:83]
	v_mfma_f32_16x16x32_bf16 v[80:83], v[230:233], v[8:11], v[80:83]
	v_mfma_f32_16x16x32_bf16 v[80:83], v[234:237], v[12:15], v[80:83]
	ds_read_b128 v[176:179], v126 offset:21760
	ds_read_b128 v[180:183], v126 offset:21824
	ds_read_b128 v[190:193], v126 offset:21888
	ds_read_b128 v[218:221], v126 offset:21952
	ds_read_b32 v214, v114 offset:320
	ds_read_b32 v215, v114 offset:324
	ds_read_b32 v216, v114 offset:328
	ds_read_b32 v217, v114 offset:332
	v_fmamk_f32 v141, v80, 0x3db504f3, v210
	v_fmamk_f32 v140, v81, 0x3db504f3, v211
	v_fmamk_f32 v143, v82, 0x3db504f3, v212
	v_fmamk_f32 v142, v83, 0x3db504f3, v213
	s_waitcnt lgkmcnt(0)
	v_mfma_f32_16x16x32_bf16 v[80:83], v[176:179], v[0:3], 0
	v_mfma_f32_16x16x32_bf16 v[80:83], v[180:183], v[4:7], v[80:83]
	v_mfma_f32_16x16x32_bf16 v[80:83], v[190:193], v[8:11], v[80:83]
	v_mfma_f32_16x16x32_bf16 v[80:83], v[218:221], v[12:15], v[80:83]
	ds_read_b128 v[222:225], v126 offset:26112
	ds_read_b128 v[226:229], v126 offset:26176
	ds_read_b128 v[230:233], v126 offset:26240
	ds_read_b128 v[234:237], v126 offset:26304
	ds_read_b32 v210, v114 offset:384
	ds_read_b32 v211, v114 offset:388
	ds_read_b32 v212, v114 offset:392
	ds_read_b32 v213, v114 offset:396
	v_fmamk_f32 v149, v80, 0x3db504f3, v214
	v_fmamk_f32 v148, v81, 0x3db504f3, v215
	v_fmamk_f32 v152, v82, 0x3db504f3, v216
	v_fmamk_f32 v151, v83, 0x3db504f3, v217
	s_waitcnt lgkmcnt(0)
	v_mfma_f32_16x16x32_bf16 v[80:83], v[222:225], v[0:3], 0
	v_mfma_f32_16x16x32_bf16 v[80:83], v[226:229], v[4:7], v[80:83]
	v_mfma_f32_16x16x32_bf16 v[80:83], v[230:233], v[8:11], v[80:83]
	v_mfma_f32_16x16x32_bf16 v[80:83], v[234:237], v[12:15], v[80:83]
	ds_read_b128 v[176:179], v126 offset:30464
	ds_read_b128 v[180:183], v126 offset:30528
	ds_read_b128 v[190:193], v126 offset:30592
	ds_read_b128 v[218:221], v126 offset:30656
	ds_read_b32 v214, v114 offset:448
	ds_read_b32 v215, v114 offset:452
	ds_read_b32 v216, v114 offset:456
	ds_read_b32 v217, v114 offset:460
	v_fmamk_f32 v154, v80, 0x3db504f3, v210
	v_fmamk_f32 v153, v81, 0x3db504f3, v211
	v_fmamk_f32 v156, v82, 0x3db504f3, v212
	v_fmamk_f32 v155, v83, 0x3db504f3, v213
	s_waitcnt lgkmcnt(0)
	v_mfma_f32_16x16x32_bf16 v[80:83], v[176:179], v[0:3], 0
	v_mfma_f32_16x16x32_bf16 v[80:83], v[180:183], v[4:7], v[80:83]
	v_mfma_f32_16x16x32_bf16 v[80:83], v[190:193], v[8:11], v[80:83]
	v_mfma_f32_16x16x32_bf16 v[80:83], v[218:221], v[12:15], v[80:83]
	s_nop 7
	v_fmamk_f32 v158, v80, 0x3db504f3, v214
	v_fmamk_f32 v157, v81, 0x3db504f3, v215
	v_fmamk_f32 v159, v82, 0x3db504f3, v216
	v_fmamk_f32 v80, v83, 0x3db504f3, v217
	s_mov_b32 s2, 0xff800000
	v_max3_f32 v81, v121, s2, v118
	v_max3_f32 v81, v81, v124, v119
	v_max3_f32 v81, v81, v122, v120
	v_max3_f32 v81, v81, v125, v123
	v_max3_f32 v81, v81, v128, v127
	v_max3_f32 v81, v81, v130, v129
	v_max3_f32 v81, v81, v136, v131
	v_max3_f32 v81, v81, v138, v139
	v_max3_f32 v81, v81, v141, v140
	v_max3_f32 v81, v81, v143, v142
	v_max3_f32 v81, v81, v149, v148
	v_max3_f32 v81, v81, v152, v151
	v_max3_f32 v81, v81, v154, v153
	v_max3_f32 v81, v81, v156, v155
	v_max3_f32 v81, v81, v158, v157
	v_max3_f32 v81, v81, v159, v80
	ds_bpermute_b32 v82, v109, v81
	v_add_u32_e32 v113, 0x80, v113
	v_add_u32_e32 v114, 0x200, v114
	s_andn2_b64 vcc, exec, s[0:1]
	s_waitcnt lgkmcnt(0)
	v_max_f32_e32 v82, v82, v82
	v_max_f32_e32 v81, v81, v82
	ds_bpermute_b32 v82, v110, v81
	s_waitcnt lgkmcnt(0)
	v_max3_f32 v81, v117, v81, v82
	v_sub_f32_e32 v82, v117, v81
	v_sub_f32_e32 v117, v118, v81
	v_mul_f32_e32 v117, 0x3fb8aa3b, v117
	v_exp_f32_e32 v147, v117
	v_sub_f32_e32 v117, v124, v81
	v_mul_f32_e32 v117, 0x3fb8aa3b, v117
	v_exp_f32_e32 v150, v117
	v_sub_f32_e32 v117, v119, v81
	v_mul_f32_e32 v117, 0x3fb8aa3b, v117
	v_exp_f32_e32 v164, v117
	v_sub_f32_e32 v117, v122, v81
	v_mul_f32_e32 v117, 0x3fb8aa3b, v117
	v_exp_f32_e32 v166, v117
	v_sub_f32_e32 v117, v120, v81
	v_mul_f32_e32 v117, 0x3fb8aa3b, v117
	v_exp_f32_e32 v172, v117
	v_sub_f32_e32 v117, v125, v81
	v_mul_f32_e32 v117, 0x3fb8aa3b, v117
	v_exp_f32_e32 v173, v117
	v_sub_f32_e32 v117, v123, v81
	v_mul_f32_e32 v117, 0x3fb8aa3b, v117
	v_exp_f32_e32 v174, v117
	v_sub_f32_e32 v117, v128, v81
	v_mul_f32_e32 v117, 0x3fb8aa3b, v117
	v_exp_f32_e32 v132, v117
	v_sub_f32_e32 v117, v127, v81
	v_mul_f32_e32 v117, 0x3fb8aa3b, v117
	v_exp_f32_e32 v133, v117
	v_sub_f32_e32 v117, v130, v81
	v_mul_f32_e32 v117, 0x3fb8aa3b, v117
	v_exp_f32_e32 v134, v117
	v_sub_f32_e32 v117, v129, v81
	v_sub_f32_e32 v83, v121, v81
	v_mul_f32_e32 v117, 0x3fb8aa3b, v117
	v_mul_f32_e32 v83, 0x3fb8aa3b, v83
	v_exp_f32_e32 v135, v117
	v_sub_f32_e32 v117, v136, v81
	v_exp_f32_e32 v146, v83
	v_mul_f32_e32 v117, 0x3fb8aa3b, v117
	v_exp_f32_e32 v136, v117
	v_sub_f32_e32 v117, v131, v81
	v_mul_f32_e32 v117, 0x3fb8aa3b, v117
	v_exp_f32_e32 v137, v117
	v_sub_f32_e32 v117, v138, v81
	v_add_f32_e32 v83, 0, v146
	v_mul_f32_e32 v117, 0x3fb8aa3b, v117
	v_add_f32_e32 v83, v147, v83
	v_exp_f32_e32 v138, v117
	v_sub_f32_e32 v117, v139, v81
	v_add_f32_e32 v83, v150, v83
	v_mul_f32_e32 v117, 0x3fb8aa3b, v117
	v_add_f32_e32 v83, v164, v83
	v_exp_f32_e32 v139, v117
	v_sub_f32_e32 v117, v141, v81
	v_add_f32_e32 v83, v166, v83
	v_mul_f32_e32 v117, 0x3fb8aa3b, v117
	v_add_f32_e32 v83, v172, v83
	v_exp_f32_e32 v124, v117
	v_sub_f32_e32 v117, v140, v81
	v_add_f32_e32 v83, v173, v83
	v_mul_f32_e32 v117, 0x3fb8aa3b, v117
	v_add_f32_e32 v83, v174, v83
	v_exp_f32_e32 v125, v117
	v_sub_f32_e32 v117, v143, v81
	v_add_f32_e32 v83, v132, v83
	v_mul_f32_e32 v117, 0x3fb8aa3b, v117
	v_add_f32_e32 v83, v133, v83
; __device__ __forceinline__ void attn_item(const Params& P, const int pass, const int item, const int wvi) {
;     ...
;     const float alpha = __expf(mrun - mnew);
;     float psum = 0.f;
; #pragma unroll
;     for (int t8 = 0; t8 < 8; ++t8)
; #pragma unroll
;       for (int j = 0; j < 4; ++j) { const float pv = __expf(sc[t8][j] - mnew); sc[t8][j] = pv; psum += pv; }
;     psum += shfl_src(psum, lane ^ 16);
;     psum += shfl_src(psum, lane ^ 32);
;     lrun = lrun * alpha + psum;
;     mrun = mnew;
; #pragma unroll
;     for (int d8 = 0; d8 < 8; ++d8)
; #pragma unroll
;       for (int j = 0; j < 4; ++j) oacc[d8][j] *= alpha;
; #pragma unroll
;     for (int kp = 0; kp < 4; ++kp) {
;       const bf16x8 pf = pack8(sc[2 * kp][0], sc[2 * kp][1], sc[2 * kp][2], sc[2 * kp][3],
;                               sc[2 * kp + 1][0], sc[2 * kp + 1][1], sc[2 * kp + 1][2], sc[2 * kp + 1][3]);
; #pragma unroll
;       for (int d8 = 0; d8 < 8; ++d8) {
;         const u16* va = Vs + (kp * 32 + fq * 4 + (fr >> 2)) * LDV + d8 * 16 + (fr & 3) * 4;
;         s16x4 v0 = ldtr(va), v1 = ldtr(va + 16 * LDV);
;         oacc[d8] = __builtin_amdgcn_mfma_f32_16x16x32_bf16(cat8(v0, v1), pf, oacc[d8], 0, 0, 0);
;       }
;     }
	v_exp_f32_e32 v126, v117
	v_sub_f32_e32 v117, v142, v81
	v_add_f32_e32 v83, v134, v83
	v_mul_f32_e32 v117, 0x3fb8aa3b, v117
	v_add_f32_e32 v83, v135, v83
	v_exp_f32_e32 v127, v117
	v_sub_f32_e32 v117, v149, v81
	v_add_f32_e32 v83, v136, v83
	v_mul_f32_e32 v117, 0x3fb8aa3b, v117
	v_add_f32_e32 v83, v137, v83
	v_exp_f32_e32 v128, v117
	v_sub_f32_e32 v117, v148, v81
	v_add_f32_e32 v83, v138, v83
	v_mul_f32_e32 v117, 0x3fb8aa3b, v117
	v_add_f32_e32 v83, v139, v83
	v_exp_f32_e32 v129, v117
	v_sub_f32_e32 v117, v152, v81
	v_add_f32_e32 v83, v124, v83
	v_mul_f32_e32 v117, 0x3fb8aa3b, v117
	v_add_f32_e32 v83, v125, v83
	v_exp_f32_e32 v130, v117
	v_sub_f32_e32 v117, v151, v81
	v_add_f32_e32 v83, v126, v83
	v_mul_f32_e32 v117, 0x3fb8aa3b, v117
	v_add_f32_e32 v83, v127, v83
	v_exp_f32_e32 v131, v117
	v_add_f32_e32 v83, v128, v83
	v_add_f32_e32 v83, v129, v83
	v_add_f32_e32 v83, v130, v83
	v_add_f32_e32 v117, v131, v83
	v_sub_f32_e32 v83, v154, v81
	v_mul_f32_e32 v83, 0x3fb8aa3b, v83
	v_exp_f32_e32 v83, v83
	v_sub_f32_e32 v80, v80, v81
	v_mul_f32_e32 v80, 0x3fb8aa3b, v80
	v_mul_f32_e32 v82, 0x3fb8aa3b, v82
	v_add_f32_e32 v118, v83, v117
	v_sub_f32_e32 v117, v153, v81
	v_mul_f32_e32 v117, 0x3fb8aa3b, v117
	v_exp_f32_e32 v117, v117
	s_nop 0
	v_add_f32_e32 v119, v117, v118
	v_sub_f32_e32 v118, v156, v81
	v_mul_f32_e32 v118, 0x3fb8aa3b, v118
	v_exp_f32_e32 v118, v118
	s_nop 0
	v_add_f32_e32 v120, v118, v119
	v_sub_f32_e32 v119, v155, v81
	v_mul_f32_e32 v119, 0x3fb8aa3b, v119
	v_exp_f32_e32 v119, v119
	s_nop 0
	v_add_f32_e32 v121, v119, v120
	v_sub_f32_e32 v120, v158, v81
	v_mul_f32_e32 v120, 0x3fb8aa3b, v120
	v_exp_f32_e32 v120, v120
	s_nop 0
	v_add_f32_e32 v122, v120, v121
	v_sub_f32_e32 v121, v157, v81
	v_mul_f32_e32 v121, 0x3fb8aa3b, v121
	v_exp_f32_e32 v121, v121
	s_nop 0
	v_add_f32_e32 v123, v121, v122
	v_sub_f32_e32 v122, v159, v81
	v_mul_f32_e32 v122, 0x3fb8aa3b, v122
	v_exp_f32_e32 v122, v122
	s_nop 0
	v_add_f32_e32 v140, v122, v123
	v_exp_f32_e32 v123, v80
	v_exp_f32_e32 v80, v82
	v_add_f32_e32 v140, v123, v140
	ds_bpermute_b32 v82, v109, v140
	v_pk_mul_f32 v[160:161], v[60:61], v[80:81] op_sel_hi:[1,0]
	v_pk_mul_f32 v[162:163], v[62:63], v[80:81] op_sel_hi:[1,0]
	v_pk_mul_f32 v[168:169], v[64:65], v[80:81] op_sel_hi:[1,0]
	v_pk_mul_f32 v[170:171], v[66:67], v[80:81] op_sel_hi:[1,0]
	s_waitcnt lgkmcnt(0)
	v_add_f32_e32 v82, v140, v82
	v_pk_mul_f32 v[140:141], v[48:49], v[80:81] op_sel_hi:[1,0]
	v_pk_mul_f32 v[48:49], v[76:77], v[80:81] op_sel_hi:[1,0]
	v_add3_u32 v77, s9, v115, v112
	ds_read_b64_tr_b16 v[62:63], v77 offset:39424
	ds_read_b64_tr_b16 v[60:61], v77 offset:34816
	ds_read_b64_tr_b16 v[64:65], v77 offset:34848
	ds_read_b64_tr_b16 v[66:67], v77 offset:39456
	ds_bpermute_b32 v148, v110, v82
	v_pk_mul_f32 v[142:143], v[50:51], v[80:81] op_sel_hi:[1,0]
	v_pk_mul_f32 v[152:153], v[56:57], v[80:81] op_sel_hi:[1,0]
	v_pk_mul_f32 v[154:155], v[58:59], v[80:81] op_sel_hi:[1,0]
	v_pk_mul_f32 v[156:157], v[52:53], v[80:81] op_sel_hi:[1,0]
	v_pk_mul_f32 v[158:159], v[54:55], v[80:81] op_sel_hi:[1,0]
	v_cvt_pk_bf16_f32 v52, v146, v147
	v_cvt_pk_bf16_f32 v53, v150, v164
	v_cvt_pk_bf16_f32 v54, v166, v172
	v_cvt_pk_bf16_f32 v55, v173, v174
	v_pk_mul_f32 v[56:57], v[72:73], v[80:81] op_sel_hi:[1,0]
	v_pk_mul_f32 v[58:59], v[74:75], v[80:81] op_sel_hi:[1,0]
	s_waitcnt lgkmcnt(0)
	v_add_f32_e32 v82, v82, v148
	v_mfma_f32_16x16x32_bf16 v[60:63], v[60:63], v[52:55], v[140:143]
	ds_read_b64_tr_b16 v[72:73], v77 offset:34880
	ds_read_b64_tr_b16 v[74:75], v77 offset:39488
	s_nop 0
	ds_read_b64_tr_b16 v[140:141], v77 offset:34912
	ds_read_b64_tr_b16 v[142:143], v77 offset:39520
	ds_read_b64_tr_b16 v[146:147], v77 offset:34944
	ds_read_b64_tr_b16 v[148:149], v77 offset:39552
	v_mfma_f32_16x16x32_bf16 v[64:67], v[64:67], v[52:55], v[152:155]
	ds_read_b64_tr_b16 v[150:151], v77 offset:34976
	s_nop 1
	ds_read_b64_tr_b16 v[152:153], v77 offset:39584
	v_pk_mul_f32 v[68:69], v[68:69], v[80:81] op_sel_hi:[1,0]
	v_pk_mul_f32 v[70:71], v[70:71], v[80:81] op_sel_hi:[1,0]
	v_pk_mul_f32 v[50:51], v[78:79], v[80:81] op_sel_hi:[1,0]
	s_waitcnt lgkmcnt(6)
	v_mfma_f32_16x16x32_bf16 v[72:75], v[72:75], v[52:55], v[156:159]
	v_add_u32_e32 v76, 0x8800, v77
	v_fmac_f32_e32 v82, v116, v80
	s_waitcnt lgkmcnt(0)
	v_mfma_f32_16x16x32_bf16 v[68:71], v[150:153], v[52:55], v[68:71]
	ds_read_b64_tr_b16 v[150:151], v77 offset:35008
	ds_read_b64_tr_b16 v[152:153], v77 offset:39616
	s_waitcnt lgkmcnt(0)
	v_mfma_f32_16x16x32_bf16 v[56:59], v[150:153], v[52:55], v[56:59]
	ds_read_b64_tr_b16 v[150:151], v77 offset:35040
	ds_read_b64_tr_b16 v[152:153], v77 offset:39648
	v_mfma_f32_16x16x32_bf16 v[140:143], v[140:143], v[52:55], v[160:163]
	v_mfma_f32_16x16x32_bf16 v[146:149], v[146:149], v[52:55], v[168:171]
	s_waitcnt lgkmcnt(0)
; __device__ __forceinline__ void attn_item(const Params& P, const int pass, const int item, const int wvi) {
;     ...
;     for (int kp = 0; kp < 4; ++kp) {
;       const bf16x8 pf = pack8(sc[2 * kp][0], sc[2 * kp][1], sc[2 * kp][2], sc[2 * kp][3],
;                               sc[2 * kp + 1][0], sc[2 * kp + 1][1], sc[2 * kp + 1][2], sc[2 * kp + 1][3]);
; #pragma unroll
;       for (int d8 = 0; d8 < 8; ++d8) {
;         const u16* va = Vs + (kp * 32 + fq * 4 + (fr >> 2)) * LDV + d8 * 16 + (fr & 3) * 4;
;         s16x4 v0 = ldtr(va), v1 = ldtr(va + 16 * LDV);
;         oacc[d8] = __builtin_amdgcn_mfma_f32_16x16x32_bf16(cat8(v0, v1), pf, oacc[d8], 0, 0, 0);
;       }
;     }
	v_mfma_f32_16x16x32_bf16 v[48:51], v[150:153], v[52:55], v[48:51]
	v_cvt_pk_bf16_f32 v52, v132, v133
	v_cvt_pk_bf16_f32 v53, v134, v135
	ds_read_b64_tr_b16 v[132:133], v77 offset:44032
	ds_read_b64_tr_b16 v[134:135], v77 offset:48640
	v_cvt_pk_bf16_f32 v54, v136, v137
	v_cvt_pk_bf16_f32 v55, v138, v139
	s_waitcnt lgkmcnt(0)
	s_nop 0
	v_mfma_f32_16x16x32_bf16 v[60:63], v[132:135], v[52:55], v[60:63]
	ds_read_b64_tr_b16 v[132:133], v77 offset:44064
	ds_read_b64_tr_b16 v[134:135], v77 offset:48672
	s_waitcnt lgkmcnt(0)
	v_mfma_f32_16x16x32_bf16 v[64:67], v[132:135], v[52:55], v[64:67]
	ds_read_b64_tr_b16 v[132:133], v77 offset:44096
	ds_read_b64_tr_b16 v[134:135], v77 offset:48704
	s_waitcnt lgkmcnt(0)
	v_mfma_f32_16x16x32_bf16 v[72:75], v[132:135], v[52:55], v[72:75]
	ds_read_b64_tr_b16 v[132:133], v77 offset:44128
	ds_read_b64_tr_b16 v[134:135], v77 offset:48736
	ds_read_b64_tr_b16 v[136:137], v77 offset:44160
	ds_read_b64_tr_b16 v[138:139], v77 offset:48768
	s_waitcnt lgkmcnt(2)
	v_mfma_f32_16x16x32_bf16 v[132:135], v[132:135], v[52:55], v[140:143]
	s_nop 2
	ds_read_b64_tr_b16 v[140:141], v77 offset:44192
	ds_read_b64_tr_b16 v[142:143], v77 offset:48800
	s_waitcnt lgkmcnt(0)
	v_mfma_f32_16x16x32_bf16 v[68:71], v[140:143], v[52:55], v[68:71]
	ds_read_b64_tr_b16 v[140:141], v77 offset:44224
	ds_read_b64_tr_b16 v[142:143], v77 offset:48832
	s_waitcnt lgkmcnt(0)
	v_mfma_f32_16x16x32_bf16 v[56:59], v[140:143], v[52:55], v[56:59]
	ds_read_b64_tr_b16 v[140:141], v77 offset:44256
	ds_read_b64_tr_b16 v[142:143], v77 offset:48864
	v_mfma_f32_16x16x32_bf16 v[136:139], v[136:139], v[52:55], v[146:149]
	s_waitcnt lgkmcnt(0)
	v_mfma_f32_16x16x32_bf16 v[48:51], v[140:143], v[52:55], v[48:51]
	v_cvt_pk_bf16_f32 v52, v124, v125
	v_cvt_pk_bf16_f32 v53, v126, v127
	ds_read_b64_tr_b16 v[124:125], v77 offset:53248
	ds_read_b64_tr_b16 v[126:127], v77 offset:57856
	v_cvt_pk_bf16_f32 v54, v128, v129
	v_cvt_pk_bf16_f32 v55, v130, v131
	v_cvt_pk_bf16_f32 v140, v83, v117
	v_cvt_pk_bf16_f32 v141, v118, v119
	s_waitcnt lgkmcnt(0)
	v_mfma_f32_16x16x32_bf16 v[60:63], v[124:127], v[52:55], v[60:63]
	ds_read_b64_tr_b16 v[124:125], v77 offset:53280
	ds_read_b64_tr_b16 v[126:127], v77 offset:57888
	v_cvt_pk_bf16_f32 v142, v120, v121
	v_cvt_pk_bf16_f32 v143, v122, v123
	s_waitcnt lgkmcnt(0)
	v_mfma_f32_16x16x32_bf16 v[64:67], v[124:127], v[52:55], v[64:67]
	ds_read_b64_tr_b16 v[124:125], v77 offset:53312
	ds_read_b64_tr_b16 v[126:127], v77 offset:57920
	s_waitcnt lgkmcnt(0)
	v_mfma_f32_16x16x32_bf16 v[72:75], v[124:127], v[52:55], v[72:75]
	ds_read_b64_tr_b16 v[124:125], v77 offset:53344
	ds_read_b64_tr_b16 v[126:127], v77 offset:57952
	ds_read_b64_tr_b16 v[128:129], v77 offset:53376
	ds_read_b64_tr_b16 v[130:131], v77 offset:57984
	s_waitcnt lgkmcnt(2)
	v_mfma_f32_16x16x32_bf16 v[124:127], v[124:127], v[52:55], v[132:135]
	s_nop 2
	ds_read_b64_tr_b16 v[132:133], v77 offset:53408
	ds_read_b64_tr_b16 v[134:135], v77 offset:58016
	s_waitcnt lgkmcnt(0)
	v_mfma_f32_16x16x32_bf16 v[68:71], v[132:135], v[52:55], v[68:71]
	ds_read_b64_tr_b16 v[132:133], v77 offset:53440
	ds_read_b64_tr_b16 v[134:135], v77 offset:58048
	s_waitcnt lgkmcnt(0)
	v_mfma_f32_16x16x32_bf16 v[132:135], v[132:135], v[52:55], v[56:59]
	s_nop 2
	ds_read_b64_tr_b16 v[56:57], v77 offset:53472
	ds_read_b64_tr_b16 v[58:59], v77 offset:58080
	v_mfma_f32_16x16x32_bf16 v[128:131], v[128:131], v[52:55], v[136:139]
	s_waitcnt lgkmcnt(0)
	v_mfma_f32_16x16x32_bf16 v[136:139], v[56:59], v[52:55], v[48:51]
	s_nop 2
	ds_read_b64_tr_b16 v[48:49], v77 offset:62464
	ds_read_b64_tr_b16 v[50:51], v76 offset:32256
	ds_read_b64_tr_b16 v[54:55], v76 offset:32288
	ds_read_b64_tr_b16 v[52:53], v77 offset:62496
	s_waitcnt lgkmcnt(0)
	v_mfma_f32_16x16x32_bf16 v[56:59], v[52:55], v[140:143], v[64:67]
	ds_read_b64_tr_b16 v[52:53], v77 offset:62528
	ds_read_b64_tr_b16 v[54:55], v76 offset:32320
	v_mfma_f32_16x16x32_bf16 v[48:51], v[48:51], v[140:143], v[60:63]
	s_nop 2
	ds_read_b64_tr_b16 v[60:61], v77 offset:62560
	ds_read_b64_tr_b16 v[62:63], v76 offset:32352
	ds_read_b64_tr_b16 v[64:65], v77 offset:62592
	ds_read_b64_tr_b16 v[66:67], v76 offset:32384
	s_waitcnt lgkmcnt(4)
	v_mfma_f32_16x16x32_bf16 v[52:55], v[52:55], v[140:143], v[72:75]
	s_nop 2
	ds_read_b64_tr_b16 v[72:73], v77 offset:62624
	ds_read_b64_tr_b16 v[74:75], v76 offset:32416
	s_waitcnt lgkmcnt(0)
	v_mfma_f32_16x16x32_bf16 v[68:71], v[72:75], v[140:143], v[68:71]
	ds_read_b64_tr_b16 v[72:73], v77 offset:62656
	ds_read_b64_tr_b16 v[74:75], v76 offset:32448
	ds_read_b64_tr_b16 v[118:119], v77 offset:62688
	ds_read_b64_tr_b16 v[120:121], v76 offset:32480
	v_mfma_f32_16x16x32_bf16 v[60:63], v[60:63], v[140:143], v[124:127]
	v_mfma_f32_16x16x32_bf16 v[64:67], v[64:67], v[140:143], v[128:131]
	s_waitcnt lgkmcnt(2)
	v_mfma_f32_16x16x32_bf16 v[72:75], v[72:75], v[140:143], v[132:135]
	s_waitcnt lgkmcnt(0)
	v_mfma_f32_16x16x32_bf16 v[76:79], v[118:121], v[140:143], v[136:139]
	s_cbranch_vccz .LBB0_626
	v_mov_b32_e32 v117, v81
	v_mov_b32_e32 v116, v82
	s_branch .LBB0_560

; __device__ __forceinline__ void ssd_item(const Params& P, const int pass, const int item, const int wvi) {
;     ...
;   unsigned yp[4][2];
; #pragma unroll
;   for (int pt = 0; pt < 4; ++pt) { yp[pt][0] = 0u; yp[pt][1] = 0u; }
;   if (w >= 4) __builtin_amdgcn_s_setprio(1);
;   SSD_ISSUE(0);
.LBB0_628:
	s_andn2_b64 vcc, exec, s[0:1]
	s_cbranch_vccnz .LBB0_439
	v_readlane_b32 s0, v245, 8
	v_readlane_b32 s1, v245, 9
	s_andn2_b64 vcc, exec, s[0:1]
	s_waitcnt vmcnt(4)
	v_mbcnt_lo_u32_b32 v46, -1, 0
	v_mbcnt_hi_u32_b32 v46, -1, v46
	s_cbranch_vccnz .LBB0_631
.LBB0_631:
	s_ashr_i32 s0, s12, 3
	v_readlane_b32 s1, v242, 5
	s_add_i32 s1, s0, s1
	s_and_b32 s6, s0, 1
	s_bfe_i32 s4, s0, 0x10000
	s_lshl_b32 s0, s1, 2
	s_lshl_b32 s3, s1, 3
	v_readlane_b32 s5, v242, 7
	s_and_b32 s2, s12, 7
	s_or_b32 s3, s3, s5
	s_and_b32 s20, s0, 56
	v_readlane_b32 s5, v245, 16
	s_or_b32 s7, s20, s2
	s_ashr_i32 s0, s3, 7
	s_and_b32 s16, s4, s5
	s_bfe_u32 s18, s1, 0x30001
	s_cmp_eq_u32 s6, 0
	s_cselect_b64 s[8:9], -1, 0
	s_and_b64 s[2:3], s[8:9], exec
	v_readlane_b32 s1, v243, 41
	s_cselect_b32 s17, s5, 3
	s_and_b32 s2, s4, s1
	s_ashr_i32 s1, s0, 31
	v_readlane_b32 s3, v243, 56
	s_lshl_b64 s[4:5], s[0:1], s3
	s_mov_b32 s3, s19
	v_add_u32_e32 v211, s48, v46
	s_lshl_b64 s[0:1], s[2:3], 7
	s_add_u32 s2, s4, s0
	v_add_u32_e32 v8, 0x400, v211
	s_addc_u32 s3, s5, s1
	v_ashrrev_i32_e32 v146, 4, v211
	v_readlane_b32 s0, v245, 25
	v_ashrrev_i32_e32 v150, 4, v8
	v_ashrrev_i32_e32 v147, 31, v146
	v_readlane_b32 s1, v245, 26
	v_ashrrev_i32_e32 v151, 31, v150
	v_lshl_add_u64 v[0:1], s[2:3], 0, v[146:147]
	v_mov_b64_e32 v[24:25], s[0:1]
	v_lshl_add_u64 v[8:9], s[2:3], 0, v[150:151]
	v_mad_u64_u32 v[2:3], s[0:1], v0, s85, v[24:25]
	v_mad_u64_u32 v[10:11], s[10:11], v8, s85, v[24:25]
	s_lshl_b32 s0, s20, 5
	s_mov_b32 s1, s19
	v_mad_i32_i24 v11, v9, s85, v11
	v_add_u32_e32 v21, 0x200, v211
	v_lshl_add_u64 v[8:9], v[10:11], 0, s[0:1]
	v_add_u32_e32 v10, 0x600, v211
	v_mad_i32_i24 v3, v1, s85, v3
	v_lshlrev_b32_e32 v20, 3, v211
	v_ashrrev_i32_e32 v148, 4, v21
	v_ashrrev_i32_e32 v152, 4, v10
	v_ashrrev_i32_e32 v154, 3, v211
	v_lshl_add_u64 v[0:1], v[2:3], 0, s[0:1]
	v_and_b32_e32 v2, 0x78, v20
	v_ashrrev_i32_e32 v149, 31, v148
	v_ashrrev_i32_e32 v153, 31, v152
	v_ashrrev_i32_e32 v155, 31, v154
	v_lshlrev_b32_e32 v144, 1, v2
	v_lshl_add_u64 v[2:3], s[2:3], 0, v[148:149]
	v_lshl_add_u64 v[10:11], s[2:3], 0, v[152:153]
	v_lshl_add_u64 v[16:17], s[2:3], 0, v[154:155]
	v_mad_u64_u32 v[4:5], s[10:11], v2, s85, v[24:25]
	v_mad_u64_u32 v[12:13], s[10:11], v10, s85, v[24:25]
	v_mad_u64_u32 v[18:19], s[10:11], v16, s85, v[24:25]
	v_mad_i32_i24 v19, v17, s85, v19
	s_lshl_b32 s10, s7, 7
	s_mov_b32 s11, s19
	v_ashrrev_i32_e32 v158, 3, v21
	v_lshl_add_u64 v[16:17], v[18:19], 0, s[10:11]
	v_and_b32_e32 v18, 56, v20
	v_ashrrev_i32_e32 v159, 31, v158
	v_lshl_add_u64 v[0:1], v[0:1], 0, v[144:145]
	v_mad_i32_i24 v5, v3, s85, v5
	v_lshlrev_b32_e32 v156, 1, v18
	v_lshl_add_u64 v[18:19], s[2:3], 0, v[158:159]
	v_add_co_u32_e32 v0, vcc, s89, v0
	v_lshl_add_u64 v[2:3], v[4:5], 0, s[0:1]
	v_mad_u64_u32 v[20:21], s[12:13], v18, s85, v[24:25]
	v_addc_co_u32_e32 v1, vcc, 0, v1, vcc
	v_lshl_add_u64 v[2:3], v[2:3], 0, v[144:145]
	v_mad_i32_i24 v21, v19, s85, v21
	v_and_b32_e32 v210, 15, v46
	v_add_co_u32_e32 v4, vcc, s89, v2
	v_lshl_add_u64 v[18:19], v[20:21], 0, s[10:11]
	s_add_u32 s10, s2, s55
	v_addc_co_u32_e32 v5, vcc, 0, v3, vcc
	v_lshl_add_u64 v[8:9], v[8:9], 0, v[144:145]
	v_mad_i32_i24 v13, v11, s85, v13
	s_addc_u32 s11, s3, s60
	v_or_b32_e32 v26, s10, v210
	v_add_co_u32_e32 v8, vcc, s89, v8
	v_lshl_add_u64 v[10:11], v[12:13], 0, s[0:1]
	s_mul_i32 s12, s11, 0x3000
	v_mad_u64_u32 v[24:25], s[10:11], v26, s85, v[24:25]
	v_lshrrev_b32_e32 v26, 1, v211
	v_addc_co_u32_e32 v9, vcc, 0, v9, vcc
	v_lshl_add_u64 v[10:11], v[10:11], 0, v[144:145]
	v_add_u32_e32 v25, s12, v25
	v_and_b32_e32 v212, 24, v26
	v_add_co_u32_e32 v12, vcc, s89, v10
	v_lshl_add_u64 v[24:25], v[24:25], 0, s[0:1]
	v_lshlrev_b32_e32 v160, 1, v212
	v_mov_b32_e32 v161, v145
	v_addc_co_u32_e32 v13, vcc, 0, v11, vcc
	v_lshl_add_u64 v[24:25], v[24:25], 0, v[160:161]
	s_mov_b64 s[0:1], 0x2800
	v_mov_b32_e32 v157, v145
	v_lshl_add_u64 v[26:27], v[24:25], 0, s[0:1]
	v_add_co_u32_e32 v24, vcc, 0x2000, v24
	v_lshl_add_u64 v[16:17], v[16:17], 0, v[156:157]
	v_lshl_add_u64 v[20:21], v[18:19], 0, v[156:157]
	v_addc_co_u32_e32 v25, vcc, 0, v25, vcc
	s_mul_i32 s32, s2, 0x3000
	v_readlane_b32 s98, v245, 25
	s_nop 3
	s_add_u32 s32, s32, s98
	v_subrev_u32_e32 v247, s32, v0
	v_subrev_u32_e32 v248, s32, v4
	v_subrev_u32_e32 v249, s32, v8
	v_subrev_u32_e32 v250, s32, v12
	v_subrev_u32_e32 v251, s32, v16
	v_subrev_u32_e32 v252, s32, v20
	v_subrev_u32_e32 v253, s32, v26
	global_load_dwordx4 v[0:3], v[0:1], off
	s_nop 0
	global_load_dwordx4 v[4:7], v[4:5], off
	s_nop 0
	global_load_dwordx4 v[8:11], v[8:9], off
	s_nop 0
	global_load_dwordx4 v[12:15], v[12:13], off
	s_nop 0
	global_load_dwordx4 v[16:19], v[16:17], off
	s_nop 0
	global_load_dwordx4 v[20:23], v[20:21], off
	s_nop 0
	global_load_dwordx4 v[36:39], v[26:27], off offset:64
	global_load_dwordx4 v[28:31], v[26:27], off offset:128
	global_load_dwordx4 v[72:75], v[24:25], off offset:2048
	s_nop 0
	global_load_dwordx4 v[24:27], v[26:27], off offset:192
	s_cmp_lt_i32 s16, 1
	s_cselect_b64 s[0:1], -1, 0
	s_cmp_gt_i32 s17, -1
	s_cselect_b64 s[10:11], -1, 0
	s_and_b64 s[0:1], s[0:1], s[10:11]
	v_cndmask_b32_e64 v32, 0, 1, s[0:1]
	v_cmp_ne_u32_e64 s[10:11], 1, v32
	s_andn2_b64 vcc, exec, s[0:1]
	s_cbranch_vccnz .LBB0_633
	s_lshr_b64 s[0:1], s[2:3], 4
	s_or_b32 s0, s0, s18
	s_lshl_b64 s[0:1], s[0:1], 7
	s_add_u32 s0, s0, s55
	s_addc_u32 s1, s1, s60
	v_mov_b32_e32 v33, s1
	v_or_b32_e32 v32, s0, v210
	v_lshlrev_b64 v[32:33], 8, v[32:33]
	v_lshl_add_u64 v[32:33], s[64:65], 0, v[32:33]
	v_lshl_add_u64 v[32:33], v[32:33], 0, v[160:161]
	global_load_dwordx4 v[84:87], v[32:33], off
	s_branch .LBB0_634
